# v19 + first-barrier census: 16 sc1 loads issued together, one wait (was 16 serialized round trips)
# baseline (speedup 1.0000x reference)
.LBB0_1290:
	v_readlane_b32 s8, v251, 47
	v_readlane_b32 s9, v251, 48
	v_readlane_b32 s2, v253, 56
	s_mov_b64 s[10:11], -1
	s_nop 2
	global_load_dword v0, v1, s[8:9] sc1
	v_readlane_b32 s8, v251, 49
	v_readlane_b32 s9, v251, 50
	s_waitcnt lgkmcnt(0)
	s_nop 3
	global_load_dword v2, v1, s[8:9] sc1
	v_readlane_b32 s8, v251, 51
	v_readlane_b32 s9, v251, 52
	s_nop 4
	global_load_dword v3, v1, s[8:9] sc1
	v_readlane_b32 s8, v251, 53
	v_readlane_b32 s9, v251, 54
	s_nop 4
	global_load_dword v4, v1, s[8:9] sc1
	v_readlane_b32 s8, v251, 55
	v_readlane_b32 s9, v251, 56
	s_nop 4
	global_load_dword v5, v1, s[8:9] sc1
	v_readlane_b32 s8, v251, 57
	v_readlane_b32 s9, v251, 58
	s_nop 4
	global_load_dword v6, v1, s[8:9] sc1
	v_readlane_b32 s8, v251, 59
	v_readlane_b32 s9, v251, 60
	s_nop 4
	global_load_dword v7, v1, s[8:9] sc1
	v_readlane_b32 s8, v251, 61
	v_readlane_b32 s9, v251, 62
	s_nop 4
	global_load_dword v8, v1, s[8:9] sc1
	v_readlane_b32 s8, v251, 63
	v_readlane_b32 s9, v252, 0
	s_nop 4
	global_load_dword v9, v1, s[8:9] sc1
	v_readlane_b32 s8, v252, 1
	v_readlane_b32 s9, v252, 2
	s_nop 4
	global_load_dword v10, v1, s[8:9] sc1
	v_readlane_b32 s8, v252, 3
	v_readlane_b32 s9, v252, 4
	s_nop 4
	global_load_dword v11, v1, s[8:9] sc1
	v_readlane_b32 s8, v252, 5
	v_readlane_b32 s9, v252, 6
	s_nop 4
	global_load_dword v12, v1, s[8:9] sc1
	v_readlane_b32 s8, v252, 7
	v_readlane_b32 s9, v252, 8
	s_nop 4
	global_load_dword v13, v1, s[8:9] sc1
	v_readlane_b32 s8, v252, 9
	v_readlane_b32 s9, v252, 10
	s_nop 4
	global_load_dword v14, v1, s[8:9] sc1
	v_readlane_b32 s8, v252, 11
	v_readlane_b32 s9, v252, 12
	s_nop 4
	global_load_dword v15, v1, s[8:9] sc1
	v_readlane_b32 s8, v252, 13
	v_readlane_b32 s9, v252, 14
	s_nop 4
	global_load_dword v16, v1, s[8:9] sc1
	s_mov_b64 s[8:9], -1
	s_waitcnt vmcnt(0)
	v_add_u32_e32 v17, v2, v0
	v_add_u32_e32 v17, v17, v3
	v_add_u32_e32 v17, v17, v4
	v_add_u32_e32 v17, v17, v5
	v_add_u32_e32 v17, v17, v6
	v_add_u32_e32 v17, v17, v7
	v_add_u32_e32 v17, v17, v8
	v_add_u32_e32 v17, v17, v9
	v_add_u32_e32 v17, v17, v10
	v_add_u32_e32 v17, v17, v11
	v_add_u32_e32 v17, v17, v12
	v_add_u32_e32 v17, v17, v13
	v_add_u32_e32 v17, v17, v14
	v_add_u32_e32 v17, v17, v15
	v_add_u32_e32 v17, v17, v16
	v_cmp_eq_u32_e32 vcc, s2, v17
	s_cbranch_vccnz .LBB0_1289
	s_and_b32 s8, s14, 0xff
	s_cmp_eq_u32 s8, 0
	s_mov_b64 s[8:9], -1
	s_mov_b64 s[12:13], -1
	s_sleep 1
	s_cbranch_scc0 .LBB0_1294
	v_readlane_b32 s8, v251, 45
	v_readlane_b32 s9, v251, 46
	s_nop 4
	global_load_dword v17, v1, s[8:9] sc1
	s_waitcnt vmcnt(0)
	v_cmp_eq_u32_e32 vcc, 0, v17
	s_cbranch_vccnz .LBB0_1296
	s_mov_b64 s[12:13], 0
	s_mov_b64 s[8:9], -1
